# loop-edge edit: grid-barrier spin loops poll without the 64-clock s_sleep between polls
# speedup vs baseline: 1.0078x; 1.0078x over previous
; __global__ void __launch_bounds__(NTHR, 2) mega(P p) {
;     ...
;   if (p.ws == nullptr) grid.sync();
.LBB0_15:
	s_nop 0
	global_load_dword v2, v0, s[6:7] offset:32 sc1
	s_waitcnt vmcnt(0)
	v_and_b32_e32 v2, 0xffff0000, v2
	v_cmp_ne_u32_e32 vcc, v2, v1
	s_or_b64 s[14:15], vcc, s[14:15]
	s_andn2_b64 exec, exec, s[14:15]
	s_cbranch_execnz .LBB0_15

; DI unsigned xb_ld(unsigned* p) { return __hip_atomic_load(p, __ATOMIC_RELAXED, __HIP_MEMORY_SCOPE_AGENT); }
; DI void xcd_barrier_complete(unsigned* bar, unsigned x, unsigned G, unsigned& nloc, unsigned& nx) {
;   unsigned sum, cnt, mine, sp = 0u;
;   for (;;) {
;     sum = 0u; cnt = 0u; mine = 0u;
; #pragma unroll
;     for (unsigned j = 0; j < 16; ++j) { const unsigned c = xb_ld(&bar[XB_XCNT(j)]); sum += c; cnt += (c > 0u) ? 1u : 0u; mine = (j == x) ? c : mine; }
;     if (sum == G) break;
;     __builtin_amdgcn_s_sleep(1);
;     if ((++sp & 255u) == 0u) { if (xb_ld(&bar[XB_TMO])) break; if (sp > XB_SPIN_CAP) { atomicAdd(&bar[XB_TMO], 1u); break; } }
;   }
;   nloc = mine > 0u ? mine : 1u; nx = cnt > 0u ? cnt : 1u;
.LBB0_79:
	global_load_dword v15, v16, s[8:9] sc1
	global_load_dword v3, v16, s[14:15] sc1
	global_load_dword v4, v16, s[16:17] sc1
	global_load_dword v5, v16, s[18:19] sc1
	global_load_dword v6, v16, s[20:21] sc1
	global_load_dword v7, v16, s[22:23] sc1
	global_load_dword v8, v16, s[24:25] sc1
	global_load_dword v9, v16, s[26:27] sc1
	global_load_dword v10, v16, s[28:29] sc1
	global_load_dword v11, v16, s[30:31] sc1
	global_load_dword v12, v16, s[34:35] sc1
	global_load_dword v13, v16, s[36:37] sc1
	global_load_dword v14, v16, s[38:39] sc1
	global_load_dword v1, v16, s[40:41] sc1
	global_load_dword v2, v16, s[42:43] sc1
	global_load_dword v0, v16, s[44:45] sc1
	s_mov_b64 s[46:47], -1
	s_mov_b64 s[48:49], -1
	s_waitcnt vmcnt(14)
	v_add_u32_e32 v17, v3, v15
	s_waitcnt vmcnt(13)
	v_add_u32_e32 v17, v17, v4
	s_waitcnt vmcnt(12)
	v_add_u32_e32 v17, v17, v5
	s_waitcnt vmcnt(11)
	v_add_u32_e32 v17, v17, v6
	s_waitcnt vmcnt(10)
	v_add_u32_e32 v17, v17, v7
	s_waitcnt vmcnt(9)
	v_add_u32_e32 v17, v17, v8
	s_waitcnt vmcnt(8)
	v_add_u32_e32 v17, v17, v9
	s_waitcnt vmcnt(7)
	v_add_u32_e32 v17, v17, v10
	s_waitcnt vmcnt(6)
	v_add_u32_e32 v17, v17, v11
	s_waitcnt vmcnt(5)
	v_add_u32_e32 v17, v17, v12
	s_waitcnt vmcnt(4)
	v_add_u32_e32 v17, v17, v13
	s_waitcnt vmcnt(3)
	v_add_u32_e32 v17, v17, v14
	s_waitcnt vmcnt(2)
	v_add_u32_e32 v17, v17, v1
	s_waitcnt vmcnt(1)
	v_add_u32_e32 v17, v17, v2
	s_waitcnt vmcnt(0)
	v_add_u32_e32 v17, v17, v0
	v_cmp_eq_u32_e32 vcc, s92, v17
	s_cbranch_vccnz .LBB0_78
	s_and_b32 s33, s3, 0xff
	s_cmp_eq_u32 s33, 0
	s_mov_b64 s[50:51], -1
	s_nop 0
	s_cbranch_scc0 .LBB0_83
	global_load_dword v17, v16, s[6:7] sc1
	s_waitcnt vmcnt(0)
	v_cmp_eq_u32_e32 vcc, 0, v17
	s_cbranch_vccnz .LBB0_85
	s_mov_b64 s[50:51], 0

; DI unsigned xb_ld(unsigned* p) { return __hip_atomic_load(p, __ATOMIC_RELAXED, __HIP_MEMORY_SCOPE_AGENT); }
; DI unsigned xb_add(unsigned* p, unsigned v) { return __hip_atomic_fetch_add(p, v, __ATOMIC_RELAXED, __HIP_MEMORY_SCOPE_AGENT); }
; #define XB_SPIN(cond, bar) do { unsigned _sp = 0; while (cond) { __builtin_amdgcn_s_sleep(1); \
;     if ((++_sp & 255u) == 0u) { if (xb_ld(&(bar)[XB_TMO])) break; if (_sp > XB_SPIN_CAP) { atomicAdd(&(bar)[XB_TMO], 1u); break; } } } } while (0)
; DI void xcd_barrier(XcdBarrier& b) {
;     ...
;       else XB_SPIN(xb_ld(&bar[XB_TOPGEN]) == tg, bar);
;       __builtin_amdgcn_fence(__ATOMIC_ACQUIRE, "agent");
;       xb_add(&bar[XB_XGEN(b.x)], 1u);
;       asm volatile("s_waitcnt vmcnt(0)" ::: "memory");
;     } else {
;       XB_SPIN(xb_ld(&bar[XB_XGEN(b.x)]) == gen, bar);
.LBB0_96:
	s_and_b32 s28, s3, 0xff
	s_mov_b64 s[26:27], -1
	s_cmp_lg_u32 s28, 0
	s_mov_b64 s[30:31], -1
	s_nop 0
	s_cbranch_scc1 .LBB0_99
	global_load_dword v3, v2, s[6:7] sc1
	s_waitcnt vmcnt(0)
	v_cmp_eq_u32_e32 vcc, 0, v3
	s_cbranch_vccnz .LBB0_101
	s_mov_b64 s[30:31], 0
	s_mov_b64 s[28:29], -1

; DI unsigned xb_ld(unsigned* p) { return __hip_atomic_load(p, __ATOMIC_RELAXED, __HIP_MEMORY_SCOPE_AGENT); }
; DI unsigned xb_add(unsigned* p, unsigned v) { return __hip_atomic_fetch_add(p, v, __ATOMIC_RELAXED, __HIP_MEMORY_SCOPE_AGENT); }
; #define XB_SPIN(cond, bar) do { unsigned _sp = 0; while (cond) { __builtin_amdgcn_s_sleep(1); \
;     if ((++_sp & 255u) == 0u) { if (xb_ld(&(bar)[XB_TMO])) break; if (_sp > XB_SPIN_CAP) { atomicAdd(&(bar)[XB_TMO], 1u); break; } } } } while (0)
; DI void xcd_barrier(XcdBarrier& b) {
;     ...
;       else XB_SPIN(xb_ld(&bar[XB_TOPGEN]) == tg, bar);
;       __builtin_amdgcn_fence(__ATOMIC_ACQUIRE, "agent");
;       xb_add(&bar[XB_XGEN(b.x)], 1u);
;       asm volatile("s_waitcnt vmcnt(0)" ::: "memory");
;     } else {
;       XB_SPIN(xb_ld(&bar[XB_XGEN(b.x)]) == gen, bar);
.LBB0_113:
	s_and_b32 s28, s3, 0xff
	s_cmp_lg_u32 s28, 0
	s_mov_b64 s[30:31], -1
	s_nop 0
	s_cbranch_scc1 .LBB0_116
	global_load_dword v1, v0, s[6:7] sc1
	s_waitcnt vmcnt(0)
	v_cmp_eq_u32_e32 vcc, 0, v1
	s_cbranch_vccnz .LBB0_118
	s_mov_b64 s[30:31], 0
	s_mov_b64 s[28:29], -1

; DI unsigned xb_ld(unsigned* p) { return __hip_atomic_load(p, __ATOMIC_RELAXED, __HIP_MEMORY_SCOPE_AGENT); }
; DI void xcd_barrier_complete(unsigned* bar, unsigned x, unsigned G, unsigned& nloc, unsigned& nx) {
;   unsigned sum, cnt, mine, sp = 0u;
;   for (;;) {
;     sum = 0u; cnt = 0u; mine = 0u;
; #pragma unroll
;     for (unsigned j = 0; j < 16; ++j) { const unsigned c = xb_ld(&bar[XB_XCNT(j)]); sum += c; cnt += (c > 0u) ? 1u : 0u; mine = (j == x) ? c : mine; }
;     if (sum == G) break;
;     __builtin_amdgcn_s_sleep(1);
;     if ((++sp & 255u) == 0u) { if (xb_ld(&bar[XB_TMO])) break; if (sp > XB_SPIN_CAP) { atomicAdd(&bar[XB_TMO], 1u); break; } }
;   }
;   nloc = mine > 0u ? mine : 1u; nx = cnt > 0u ? cnt : 1u;
.LBB0_152:
	v_readlane_b32 s16, v222, 1
	v_readlane_b32 s17, v222, 2
	s_mov_b64 s[38:39], -1
	s_mov_b64 s[42:43], -1
	s_nop 2
	global_load_dword v0, v96, s[16:17] sc1
	v_readlane_b32 s16, v222, 3
	v_readlane_b32 s17, v222, 4
	s_nop 4
	global_load_dword v1, v96, s[16:17] sc1
	v_readlane_b32 s16, v222, 5
	v_readlane_b32 s17, v222, 6
	s_waitcnt vmcnt(0)
	v_add_u32_e32 v16, v1, v0
	s_nop 2
	global_load_dword v2, v96, s[16:17] sc1
	v_readlane_b32 s16, v222, 7
	v_readlane_b32 s17, v222, 8
	s_waitcnt vmcnt(0)
	v_add_u32_e32 v16, v16, v2
	s_nop 2
	global_load_dword v3, v96, s[16:17] sc1
	v_readlane_b32 s16, v222, 9
	v_readlane_b32 s17, v222, 10
	s_waitcnt vmcnt(0)
	v_add_u32_e32 v16, v16, v3
	s_nop 2
	global_load_dword v4, v96, s[16:17] sc1
	v_readlane_b32 s16, v222, 11
	v_readlane_b32 s17, v222, 12
	s_waitcnt vmcnt(0)
	v_add_u32_e32 v16, v16, v4
	s_nop 2
	global_load_dword v5, v96, s[16:17] sc1
	v_readlane_b32 s16, v222, 13
	v_readlane_b32 s17, v222, 14
	s_waitcnt vmcnt(0)
	v_add_u32_e32 v16, v16, v5
	s_nop 2
	global_load_dword v6, v96, s[16:17] sc1
	v_readlane_b32 s16, v222, 15
	v_readlane_b32 s17, v222, 16
	s_waitcnt vmcnt(0)
	v_add_u32_e32 v16, v16, v6
	s_nop 2
	global_load_dword v7, v96, s[16:17] sc1
	v_readlane_b32 s16, v222, 17
	v_readlane_b32 s17, v222, 18
	s_waitcnt vmcnt(0)
	v_add_u32_e32 v16, v16, v7
	s_nop 2
	global_load_dword v8, v96, s[16:17] sc1
	v_readlane_b32 s16, v222, 19
	v_readlane_b32 s17, v222, 20
	s_waitcnt vmcnt(0)
	v_add_u32_e32 v16, v16, v8
	s_nop 2
	global_load_dword v9, v96, s[16:17] sc1
	v_readlane_b32 s16, v222, 21
	v_readlane_b32 s17, v222, 22
	s_waitcnt vmcnt(0)
	v_add_u32_e32 v16, v16, v9
	s_nop 2
	global_load_dword v10, v96, s[16:17] sc1
	v_readlane_b32 s16, v222, 23
	v_readlane_b32 s17, v222, 24
	s_waitcnt vmcnt(0)
	v_add_u32_e32 v16, v16, v10
	s_nop 2
	global_load_dword v11, v96, s[16:17] sc1
	v_readlane_b32 s16, v222, 25
	v_readlane_b32 s17, v222, 26
	s_waitcnt vmcnt(0)
	v_add_u32_e32 v16, v16, v11
	s_nop 2
	global_load_dword v12, v96, s[16:17] sc1
	v_readlane_b32 s16, v222, 27
	v_readlane_b32 s17, v222, 28
	s_waitcnt vmcnt(0)
	v_add_u32_e32 v16, v16, v12
	s_nop 2
	global_load_dword v13, v96, s[16:17] sc1
	v_readlane_b32 s16, v222, 29
	v_readlane_b32 s17, v222, 30
	s_waitcnt vmcnt(0)
	v_add_u32_e32 v16, v16, v13
	s_nop 2
	global_load_dword v14, v96, s[16:17] sc1
	v_readlane_b32 s16, v222, 31
	v_readlane_b32 s17, v222, 32
	s_waitcnt vmcnt(0)
	v_add_u32_e32 v16, v16, v14
	s_nop 2
	global_load_dword v15, v96, s[16:17] sc1
	v_readlane_b32 s16, v218, 43
	s_waitcnt vmcnt(0)
	v_add_u32_e32 v16, v16, v15
	v_cmp_eq_u32_e32 vcc, s16, v16
	s_cbranch_vccnz .LBB0_151
	s_and_b32 s16, s15, 0xff
	s_cmp_eq_u32 s16, 0
	s_mov_b64 s[44:45], -1
	s_nop 0
	s_cbranch_scc0 .LBB0_156
	v_readlane_b32 s16, v223, 63
	v_readlane_b32 s17, v222, 0
	s_nop 4
	global_load_dword v16, v96, s[16:17] sc1
	s_waitcnt vmcnt(0)
	v_cmp_eq_u32_e32 vcc, 0, v16
	s_cbranch_vccnz .LBB0_158
	s_mov_b64 s[44:45], 0

; DI unsigned xb_ld(unsigned* p) { return __hip_atomic_load(p, __ATOMIC_RELAXED, __HIP_MEMORY_SCOPE_AGENT); }
; DI unsigned xb_add(unsigned* p, unsigned v) { return __hip_atomic_fetch_add(p, v, __ATOMIC_RELAXED, __HIP_MEMORY_SCOPE_AGENT); }
; #define XB_SPIN(cond, bar) do { unsigned _sp = 0; while (cond) { __builtin_amdgcn_s_sleep(1); \
;     if ((++_sp & 255u) == 0u) { if (xb_ld(&(bar)[XB_TMO])) break; if (_sp > XB_SPIN_CAP) { atomicAdd(&(bar)[XB_TMO], 1u); break; } } } } while (0)
; DI void xcd_barrier(XcdBarrier& b) {
;     ...
;       else XB_SPIN(xb_ld(&bar[XB_TOPGEN]) == tg, bar);
;       __builtin_amdgcn_fence(__ATOMIC_ACQUIRE, "agent");
;       xb_add(&bar[XB_XGEN(b.x)], 1u);
;       asm volatile("s_waitcnt vmcnt(0)" ::: "memory");
;     } else {
;       XB_SPIN(xb_ld(&bar[XB_XGEN(b.x)]) == gen, bar);
.LBB0_168:
	s_and_b32 s16, s15, 0xff
	s_mov_b64 s[46:47], -1
	s_cmp_lg_u32 s16, 0
	s_mov_b64 s[52:53], -1
	s_nop 0
	s_cbranch_scc1 .LBB0_171
	v_readlane_b32 s16, v223, 63
	v_readlane_b32 s17, v222, 0
	s_nop 4
	global_load_dword v1, v96, s[16:17] sc1
	s_waitcnt vmcnt(0)
	v_cmp_eq_u32_e32 vcc, 0, v1
	s_cbranch_vccnz .LBB0_173
	s_mov_b64 s[52:53], 0
	s_mov_b64 s[48:49], -1

; DI unsigned xb_ld(unsigned* p) { return __hip_atomic_load(p, __ATOMIC_RELAXED, __HIP_MEMORY_SCOPE_AGENT); }
; DI unsigned xb_add(unsigned* p, unsigned v) { return __hip_atomic_fetch_add(p, v, __ATOMIC_RELAXED, __HIP_MEMORY_SCOPE_AGENT); }
; #define XB_SPIN(cond, bar) do { unsigned _sp = 0; while (cond) { __builtin_amdgcn_s_sleep(1); \
;     if ((++_sp & 255u) == 0u) { if (xb_ld(&(bar)[XB_TMO])) break; if (_sp > XB_SPIN_CAP) { atomicAdd(&(bar)[XB_TMO], 1u); break; } } } } while (0)
; DI void xcd_barrier(XcdBarrier& b) {
;     ...
;       else XB_SPIN(xb_ld(&bar[XB_TOPGEN]) == tg, bar);
;       __builtin_amdgcn_fence(__ATOMIC_ACQUIRE, "agent");
;       xb_add(&bar[XB_XGEN(b.x)], 1u);
;       asm volatile("s_waitcnt vmcnt(0)" ::: "memory");
;     } else {
;       XB_SPIN(xb_ld(&bar[XB_XGEN(b.x)]) == gen, bar);
.LBB0_185:
	s_and_b32 s16, s15, 0xff
	s_mov_b64 s[48:49], -1
	s_cmp_lg_u32 s16, 0
	s_mov_b64 s[54:55], -1
	s_nop 0
	s_cbranch_scc1 .LBB0_188
	v_readlane_b32 s16, v223, 63
	v_readlane_b32 s17, v222, 0
	s_nop 4
	global_load_dword v0, v96, s[16:17] sc1
	s_waitcnt vmcnt(0)
	v_cmp_eq_u32_e32 vcc, 0, v0
	s_cbranch_vccnz .LBB0_190
	s_mov_b64 s[54:55], 0
	s_mov_b64 s[52:53], -1

; DI unsigned xb_ld(unsigned* p) { return __hip_atomic_load(p, __ATOMIC_RELAXED, __HIP_MEMORY_SCOPE_AGENT); }
; DI void xcd_barrier_complete(unsigned* bar, unsigned x, unsigned G, unsigned& nloc, unsigned& nx) {
;   unsigned sum, cnt, mine, sp = 0u;
;   for (;;) {
;     sum = 0u; cnt = 0u; mine = 0u;
; #pragma unroll
;     for (unsigned j = 0; j < 16; ++j) { const unsigned c = xb_ld(&bar[XB_XCNT(j)]); sum += c; cnt += (c > 0u) ? 1u : 0u; mine = (j == x) ? c : mine; }
;     if (sum == G) break;
;     __builtin_amdgcn_s_sleep(1);
;     if ((++sp & 255u) == 0u) { if (xb_ld(&bar[XB_TMO])) break; if (sp > XB_SPIN_CAP) { atomicAdd(&bar[XB_TMO], 1u); break; } }
;   }
;   nloc = mine > 0u ? mine : 1u; nx = cnt > 0u ? cnt : 1u;
.LBB0_526:
	v_readlane_b32 s16, v222, 1
	v_readlane_b32 s17, v222, 2
	s_mov_b64 s[38:39], -1
	s_mov_b64 s[40:41], -1
	s_nop 2
	global_load_dword v0, v96, s[16:17] sc1
	v_readlane_b32 s16, v222, 3
	v_readlane_b32 s17, v222, 4
	s_nop 4
	global_load_dword v1, v96, s[16:17] sc1
	v_readlane_b32 s16, v222, 5
	v_readlane_b32 s17, v222, 6
	s_waitcnt vmcnt(0)
	v_add_u32_e32 v16, v1, v0
	s_nop 2
	global_load_dword v2, v96, s[16:17] sc1
	v_readlane_b32 s16, v222, 7
	v_readlane_b32 s17, v222, 8
	s_waitcnt vmcnt(0)
	v_add_u32_e32 v16, v16, v2
	s_nop 2
	global_load_dword v3, v96, s[16:17] sc1
	v_readlane_b32 s16, v222, 9
	v_readlane_b32 s17, v222, 10
	s_waitcnt vmcnt(0)
	v_add_u32_e32 v16, v16, v3
	s_nop 2
	global_load_dword v4, v96, s[16:17] sc1
	v_readlane_b32 s16, v222, 11
	v_readlane_b32 s17, v222, 12
	s_waitcnt vmcnt(0)
	v_add_u32_e32 v16, v16, v4
	s_nop 2
	global_load_dword v5, v96, s[16:17] sc1
	v_readlane_b32 s16, v222, 13
	v_readlane_b32 s17, v222, 14
	s_waitcnt vmcnt(0)
	v_add_u32_e32 v16, v16, v5
	s_nop 2
	global_load_dword v6, v96, s[16:17] sc1
	v_readlane_b32 s16, v222, 15
	v_readlane_b32 s17, v222, 16
	s_waitcnt vmcnt(0)
	v_add_u32_e32 v16, v16, v6
	s_nop 2
	global_load_dword v7, v96, s[16:17] sc1
	v_readlane_b32 s16, v222, 17
	v_readlane_b32 s17, v222, 18
	s_waitcnt vmcnt(0)
	v_add_u32_e32 v16, v16, v7
	s_nop 2
	global_load_dword v8, v96, s[16:17] sc1
	v_readlane_b32 s16, v222, 19
	v_readlane_b32 s17, v222, 20
	s_waitcnt vmcnt(0)
	v_add_u32_e32 v16, v16, v8
	s_nop 2
	global_load_dword v9, v96, s[16:17] sc1
	v_readlane_b32 s16, v222, 21
	v_readlane_b32 s17, v222, 22
	s_waitcnt vmcnt(0)
	v_add_u32_e32 v16, v16, v9
	s_nop 2
	global_load_dword v10, v96, s[16:17] sc1
	v_readlane_b32 s16, v222, 23
	v_readlane_b32 s17, v222, 24
	s_waitcnt vmcnt(0)
	v_add_u32_e32 v16, v16, v10
	s_nop 2
	global_load_dword v11, v96, s[16:17] sc1
	v_readlane_b32 s16, v222, 25
	v_readlane_b32 s17, v222, 26
	s_waitcnt vmcnt(0)
	v_add_u32_e32 v16, v16, v11
	s_nop 2
	global_load_dword v12, v96, s[16:17] sc1
	v_readlane_b32 s16, v222, 27
	v_readlane_b32 s17, v222, 28
	s_waitcnt vmcnt(0)
	v_add_u32_e32 v16, v16, v12
	s_nop 2
	global_load_dword v13, v96, s[16:17] sc1
	v_readlane_b32 s16, v222, 29
	v_readlane_b32 s17, v222, 30
	s_waitcnt vmcnt(0)
	v_add_u32_e32 v16, v16, v13
	s_nop 2
	global_load_dword v14, v96, s[16:17] sc1
	v_readlane_b32 s16, v222, 31
	v_readlane_b32 s17, v222, 32
	s_waitcnt vmcnt(0)
	v_add_u32_e32 v16, v16, v14
	s_nop 2
	global_load_dword v15, v96, s[16:17] sc1
	v_readlane_b32 s16, v218, 43
	s_waitcnt vmcnt(0)
	v_add_u32_e32 v16, v16, v15
	v_cmp_eq_u32_e32 vcc, s16, v16
	s_cbranch_vccnz .LBB0_525
	s_and_b32 s16, s15, 0xff
	s_cmp_eq_u32 s16, 0
	s_mov_b64 s[42:43], -1
	s_nop 0
	s_cbranch_scc0 .LBB0_530
	v_readlane_b32 s16, v223, 63
	v_readlane_b32 s17, v222, 0
	s_nop 4
	global_load_dword v16, v96, s[16:17] sc1
	s_waitcnt vmcnt(0)
	v_cmp_eq_u32_e32 vcc, 0, v16
	s_cbranch_vccnz .LBB0_532
	s_mov_b64 s[42:43], 0

; DI unsigned xb_ld(unsigned* p) { return __hip_atomic_load(p, __ATOMIC_RELAXED, __HIP_MEMORY_SCOPE_AGENT); }
; DI unsigned xb_add(unsigned* p, unsigned v) { return __hip_atomic_fetch_add(p, v, __ATOMIC_RELAXED, __HIP_MEMORY_SCOPE_AGENT); }
; #define XB_SPIN(cond, bar) do { unsigned _sp = 0; while (cond) { __builtin_amdgcn_s_sleep(1); \
;     if ((++_sp & 255u) == 0u) { if (xb_ld(&(bar)[XB_TMO])) break; if (_sp > XB_SPIN_CAP) { atomicAdd(&(bar)[XB_TMO], 1u); break; } } } } while (0)
; DI void xcd_barrier(XcdBarrier& b) {
;     ...
;       else XB_SPIN(xb_ld(&bar[XB_TOPGEN]) == tg, bar);
;       __builtin_amdgcn_fence(__ATOMIC_ACQUIRE, "agent");
;       xb_add(&bar[XB_XGEN(b.x)], 1u);
;       asm volatile("s_waitcnt vmcnt(0)" ::: "memory");
;     } else {
;       XB_SPIN(xb_ld(&bar[XB_XGEN(b.x)]) == gen, bar);
.LBB0_542:
	s_and_b32 s16, s15, 0xff
	s_mov_b64 s[44:45], -1
	s_cmp_lg_u32 s16, 0
	s_mov_b64 s[48:49], -1
	s_nop 0
	s_cbranch_scc1 .LBB0_545
	v_readlane_b32 s16, v223, 63
	v_readlane_b32 s17, v222, 0
	s_nop 4
	global_load_dword v1, v96, s[16:17] sc1
	s_waitcnt vmcnt(0)
	v_cmp_eq_u32_e32 vcc, 0, v1
	s_cbranch_vccnz .LBB0_547
	s_mov_b64 s[48:49], 0
	s_mov_b64 s[46:47], -1

; DI unsigned xb_ld(unsigned* p) { return __hip_atomic_load(p, __ATOMIC_RELAXED, __HIP_MEMORY_SCOPE_AGENT); }
; DI unsigned xb_add(unsigned* p, unsigned v) { return __hip_atomic_fetch_add(p, v, __ATOMIC_RELAXED, __HIP_MEMORY_SCOPE_AGENT); }
; #define XB_SPIN(cond, bar) do { unsigned _sp = 0; while (cond) { __builtin_amdgcn_s_sleep(1); \
;     if ((++_sp & 255u) == 0u) { if (xb_ld(&(bar)[XB_TMO])) break; if (_sp > XB_SPIN_CAP) { atomicAdd(&(bar)[XB_TMO], 1u); break; } } } } while (0)
; DI void xcd_barrier(XcdBarrier& b) {
;     ...
;       else XB_SPIN(xb_ld(&bar[XB_TOPGEN]) == tg, bar);
;       __builtin_amdgcn_fence(__ATOMIC_ACQUIRE, "agent");
;       xb_add(&bar[XB_XGEN(b.x)], 1u);
;       asm volatile("s_waitcnt vmcnt(0)" ::: "memory");
;     } else {
;       XB_SPIN(xb_ld(&bar[XB_XGEN(b.x)]) == gen, bar);
.LBB0_559:
	s_and_b32 s16, s15, 0xff
	s_mov_b64 s[46:47], -1
	s_cmp_lg_u32 s16, 0
	s_mov_b64 s[52:53], -1
	s_nop 0
	s_cbranch_scc1 .LBB0_562
	v_readlane_b32 s16, v223, 63
	v_readlane_b32 s17, v222, 0
	s_nop 4
	global_load_dword v0, v96, s[16:17] sc1
	s_waitcnt vmcnt(0)
	v_cmp_eq_u32_e32 vcc, 0, v0
	s_cbranch_vccnz .LBB0_564
	s_mov_b64 s[52:53], 0
	s_mov_b64 s[48:49], -1

; DI unsigned xb_ld(unsigned* p) { return __hip_atomic_load(p, __ATOMIC_RELAXED, __HIP_MEMORY_SCOPE_AGENT); }
; DI void xcd_barrier_complete(unsigned* bar, unsigned x, unsigned G, unsigned& nloc, unsigned& nx) {
;   unsigned sum, cnt, mine, sp = 0u;
;   for (;;) {
;     sum = 0u; cnt = 0u; mine = 0u;
; #pragma unroll
;     for (unsigned j = 0; j < 16; ++j) { const unsigned c = xb_ld(&bar[XB_XCNT(j)]); sum += c; cnt += (c > 0u) ? 1u : 0u; mine = (j == x) ? c : mine; }
;     if (sum == G) break;
;     __builtin_amdgcn_s_sleep(1);
;     if ((++sp & 255u) == 0u) { if (xb_ld(&bar[XB_TMO])) break; if (sp > XB_SPIN_CAP) { atomicAdd(&bar[XB_TMO], 1u); break; } }
;   }
;   nloc = mine > 0u ? mine : 1u; nx = cnt > 0u ? cnt : 1u;
.LBB0_983:
	v_readlane_b32 s16, v220, 39
	v_readlane_b32 s17, v220, 40
	s_nop 4
	global_load_dword v10, v96, s[16:17] offset:1024 sc1
	global_load_dword v0, v96, s[16:17] offset:1280 sc1
	global_load_dword v1, v96, s[16:17] offset:1536 sc1
	global_load_dword v2, v96, s[16:17] offset:1792 sc1
	global_load_dword v3, v96, s[16:17] offset:2048 sc1
	global_load_dword v4, v96, s[16:17] offset:2304 sc1
	global_load_dword v5, v96, s[16:17] offset:2560 sc1
	global_load_dword v6, v96, s[16:17] offset:2816 sc1
	global_load_dword v7, v96, s[16:17] offset:3072 sc1
	global_load_dword v8, v96, s[16:17] offset:3328 sc1
	global_load_dword v9, v96, s[16:17] offset:3584 sc1
	global_load_dword v11, v96, s[16:17] offset:3840 sc1
	v_readlane_b32 s16, v221, 57
	v_readlane_b32 s17, v221, 58
	s_mov_b64 s[38:39], -1
	s_mov_b64 s[40:41], -1
	s_waitcnt vmcnt(10)
	v_add_u32_e32 v16, v0, v10
	s_nop 0
	global_load_dword v12, v96, s[16:17] sc1
	v_readlane_b32 s16, v221, 59
	v_readlane_b32 s17, v221, 60
	s_waitcnt vmcnt(10)
	v_add_u32_e32 v16, v16, v1
	s_waitcnt vmcnt(9)
	v_add_u32_e32 v16, v16, v2
	s_waitcnt vmcnt(8)
	v_add_u32_e32 v16, v16, v3
	s_waitcnt vmcnt(7)
	v_add_u32_e32 v16, v16, v4
	s_waitcnt vmcnt(6)
	v_add_u32_e32 v16, v16, v5
	global_load_dword v13, v96, s[16:17] sc1
	v_readlane_b32 s16, v221, 61
	v_readlane_b32 s17, v221, 62
	s_waitcnt vmcnt(6)
	v_add_u32_e32 v16, v16, v6
	s_waitcnt vmcnt(5)
	v_add_u32_e32 v16, v16, v7
	s_waitcnt vmcnt(4)
	v_add_u32_e32 v16, v16, v8
	s_waitcnt vmcnt(3)
	v_add_u32_e32 v16, v16, v9
	s_waitcnt vmcnt(2)
	v_add_u32_e32 v16, v16, v11
	global_load_dword v14, v96, s[16:17] sc1
	v_readlane_b32 s16, v221, 63
	v_readlane_b32 s17, v220, 0
	s_waitcnt vmcnt(2)
	v_add_u32_e32 v16, v16, v12
	s_nop 2
	global_load_dword v15, v96, s[16:17] sc1
	v_readlane_b32 s16, v218, 19
	s_waitcnt vmcnt(2)
	v_add_u32_e32 v16, v16, v13
	s_waitcnt vmcnt(1)
	v_add_u32_e32 v16, v16, v14
	s_waitcnt vmcnt(0)
	v_add_u32_e32 v16, v16, v15
	v_cmp_eq_u32_e32 vcc, s16, v16
	s_cbranch_vccnz .LBB0_982
	s_and_b32 s16, s15, 0xff
	s_cmp_eq_u32 s16, 0
	s_mov_b64 s[42:43], -1
	s_nop 0
	s_cbranch_scc0 .LBB0_987
	v_readlane_b32 s16, v221, 55
	v_readlane_b32 s17, v221, 56
	s_nop 4
	global_load_dword v16, v96, s[16:17] sc1
	s_waitcnt vmcnt(0)
	v_cmp_eq_u32_e32 vcc, 0, v16
	s_cbranch_vccnz .LBB0_989
	s_mov_b64 s[42:43], 0

; DI unsigned xb_ld(unsigned* p) { return __hip_atomic_load(p, __ATOMIC_RELAXED, __HIP_MEMORY_SCOPE_AGENT); }
; DI unsigned xb_add(unsigned* p, unsigned v) { return __hip_atomic_fetch_add(p, v, __ATOMIC_RELAXED, __HIP_MEMORY_SCOPE_AGENT); }
; #define XB_SPIN(cond, bar) do { unsigned _sp = 0; while (cond) { __builtin_amdgcn_s_sleep(1); \
;     if ((++_sp & 255u) == 0u) { if (xb_ld(&(bar)[XB_TMO])) break; if (_sp > XB_SPIN_CAP) { atomicAdd(&(bar)[XB_TMO], 1u); break; } } } } while (0)
; DI void xcd_barrier(XcdBarrier& b) {
;     ...
;       else XB_SPIN(xb_ld(&bar[XB_TOPGEN]) == tg, bar);
;       __builtin_amdgcn_fence(__ATOMIC_ACQUIRE, "agent");
;       xb_add(&bar[XB_XGEN(b.x)], 1u);
;       asm volatile("s_waitcnt vmcnt(0)" ::: "memory");
;     } else {
;       XB_SPIN(xb_ld(&bar[XB_XGEN(b.x)]) == gen, bar);
.LBB0_1002:
	s_and_b32 s16, s15, 0xff
	s_mov_b64 s[44:45], -1
	s_cmp_lg_u32 s16, 0
	s_mov_b64 s[48:49], -1
	s_nop 0
	s_cbranch_scc1 .LBB0_1005
	v_readlane_b32 s16, v221, 55
	v_readlane_b32 s17, v221, 56
	s_nop 4
	global_load_dword v0, v96, s[16:17] sc1
	s_waitcnt vmcnt(0)
	v_cmp_eq_u32_e32 vcc, 0, v0
	s_cbranch_vccnz .LBB0_1007
	s_mov_b64 s[48:49], 0
	s_mov_b64 s[46:47], -1

; DI unsigned xb_ld(unsigned* p) { return __hip_atomic_load(p, __ATOMIC_RELAXED, __HIP_MEMORY_SCOPE_AGENT); }
; DI unsigned xb_add(unsigned* p, unsigned v) { return __hip_atomic_fetch_add(p, v, __ATOMIC_RELAXED, __HIP_MEMORY_SCOPE_AGENT); }
; #define XB_SPIN(cond, bar) do { unsigned _sp = 0; while (cond) { __builtin_amdgcn_s_sleep(1); \
;     if ((++_sp & 255u) == 0u) { if (xb_ld(&(bar)[XB_TMO])) break; if (_sp > XB_SPIN_CAP) { atomicAdd(&(bar)[XB_TMO], 1u); break; } } } } while (0)
; DI void xcd_barrier(XcdBarrier& b) {
;     ...
;       else XB_SPIN(xb_ld(&bar[XB_TOPGEN]) == tg, bar);
;       __builtin_amdgcn_fence(__ATOMIC_ACQUIRE, "agent");
;       xb_add(&bar[XB_XGEN(b.x)], 1u);
;       asm volatile("s_waitcnt vmcnt(0)" ::: "memory");
;     } else {
;       XB_SPIN(xb_ld(&bar[XB_XGEN(b.x)]) == gen, bar);
.LBB0_1019:
	s_and_b32 s16, s15, 0xff
	s_mov_b64 s[46:47], -1
	s_cmp_lg_u32 s16, 0
	s_mov_b64 s[52:53], -1
	s_nop 0
	s_cbranch_scc1 .LBB0_1022
	v_readlane_b32 s16, v221, 55
	v_readlane_b32 s17, v221, 56
	s_nop 4
	global_load_dword v0, v96, s[16:17] sc1
	s_waitcnt vmcnt(0)
	v_cmp_eq_u32_e32 vcc, 0, v0
	s_cbranch_vccnz .LBB0_1024
	s_mov_b64 s[52:53], 0
	s_mov_b64 s[48:49], -1
